# ssm_b: preload the 16 B*u LDS values of each 16-token sub-block before the recurrence (was ds_read + lgkmcnt(0) in every step)
# speedup vs baseline: 1.0395x; 1.0157x over previous
.LBB0_230:
	s_waitcnt lgkmcnt(0)
	v_mfma_f32_16x16x16_bf16 v[50:53], v[46:47], v[10:11], 0
	v_add_u32_e32 v49, 0x4000, v119
	v_add_u32_e32 v97, 0x4800, v119
	s_and_b64 vcc, exec, s[38:39]
	v_mfma_f32_16x16x16_bf16 v[126:129], v[46:47], v[18:19], 0
	v_mfma_f32_16x16x16_bf16 v[130:133], v[46:47], v[12:13], 0
	s_nop 2
	v_mov_b32_e32 v108, v50
	s_nop 2
	v_mov_b32_e32 v109, v126
	v_mov_b32_e32 v126, v51
	v_mov_b32_e32 v138, v52
	v_mov_b32_e32 v139, v128
	v_mov_b32_e32 v128, v53
	v_mfma_f32_16x16x16_bf16 v[50:53], v[46:47], v[20:21], 0
	v_mov_b32_e32 v134, v130
	s_nop 6
	v_mov_b32_e32 v135, v50
	v_mov_b32_e32 v50, v131
	ds_write2_b64 v49, v[126:127], v[50:51] offset0:194 offset1:210
	v_mov_b32_e32 v50, v132
	v_mov_b32_e32 v51, v52
	v_mov_b32_e32 v52, v133
	ds_write2_b64 v49, v[108:109], v[134:135] offset0:128 offset1:144
	v_mfma_f32_16x16x16_bf16 v[134:137], v[46:47], v[14:15], 0
	ds_write2_b64 v97, v[138:139], v[50:51] offset0:4 offset1:20
	ds_write2_b64 v97, v[128:129], v[52:53] offset0:70 offset1:86
	v_mfma_f32_16x16x16_bf16 v[130:133], v[46:47], v[22:23], 0
	v_mfma_f32_16x16x16_bf16 v[50:53], v[46:47], v[16:17], 0
	s_nop 3
	v_mov_b32_e32 v108, v134
	s_nop 1
	v_mov_b32_e32 v109, v130
	v_mov_b32_e32 v130, v135
	v_mfma_f32_16x16x16_bf16 v[126:129], v[46:47], v[24:25], 0
	v_mov_b32_e32 v134, v136
	v_mov_b32_e32 v46, v50
	v_mov_b32_e32 v135, v132
	v_mov_b32_e32 v132, v137
	s_nop 3
	v_mov_b32_e32 v47, v126
	ds_write2_b64 v49, v[108:109], v[46:47] offset0:160 offset1:176
	v_mov_b32_e32 v126, v51
	v_mov_b32_e32 v46, v52
	v_mov_b32_e32 v47, v128
	v_mov_b32_e32 v128, v53
	ds_write2_b64 v49, v[130:131], v[126:127] offset0:226 offset1:242
	ds_write2_b64 v97, v[134:135], v[46:47] offset0:36 offset1:52
	ds_write2_b64 v97, v[132:133], v[128:129] offset0:102 offset1:118
	s_waitcnt lgkmcnt(0)
	ds_read_b64 v[206:207], v114 offset:17408
	ds_read_b64 v[208:209], v114 offset:17936
	ds_read_b64 v[210:211], v114 offset:18464
	ds_read_b64 v[212:213], v114 offset:18992
	ds_read_b64 v[214:215], v114 offset:19520
	ds_read_b64 v[216:217], v114 offset:20048
	ds_read_b64 v[218:219], v114 offset:20576
	ds_read_b64 v[220:221], v114 offset:21104
	ds_read_b64 v[222:223], v114 offset:21632
	ds_read_b64 v[224:225], v114 offset:22160
	ds_read_b64 v[226:227], v114 offset:22688
	ds_read_b64 v[228:229], v114 offset:23216
	ds_read_b64 v[230:231], v114 offset:23744
	ds_read_b64 v[232:233], v114 offset:24272
	ds_read_b64 v[234:235], v114 offset:24800
	s_waitcnt lgkmcnt(7)
	ds_read_b64 v[236:237], v114 offset:25328
	v_pk_mul_f32 v[48:49], v[94:95], v[48:49] op_sel_hi:[1,0]
	s_nop 0
	v_pk_fma_f32 v[50:51], v[78:79], v[0:1], v[48:49] neg_lo:[0,0,1] neg_hi:[0,0,1]
	v_pk_fma_f32 v[48:49], v[78:79], v[0:1], v[48:49] op_sel_hi:[1,0,1]
	s_nop 0
	v_mov_b32_e32 v51, v49
	v_pk_add_f32 v[46:47], v[50:51], v[206:207]
	s_nop 0
	v_cvt_pk_bf16_f32 v0, v46, v47
	ds_write_b32 v121, v0 offset:25856
	v_pk_mul_f32 v[50:51], v[80:81], v[46:47]
	s_nop 0
	v_pk_fma_f32 v[52:53], v[92:93], v[46:47], v[50:51] op_sel:[0,0,1] op_sel_hi:[1,1,0]
	v_pk_fma_f32 v[46:47], v[92:93], v[46:47], v[50:51] op_sel:[0,0,1] op_sel_hi:[1,1,0] neg_lo:[0,0,1] neg_hi:[0,0,1]
	s_nop 0
	v_mov_b32_e32 v47, v53
	v_pk_add_f32 v[46:47], v[46:47], v[208:209]
	s_nop 0
	v_cvt_pk_bf16_f32 v0, v46, v47
	ds_write_b32 v121, v0 offset:26128
	v_pk_mul_f32 v[50:51], v[80:81], v[46:47]
	s_nop 0
	v_pk_fma_f32 v[52:53], v[92:93], v[46:47], v[50:51] op_sel:[0,0,1] op_sel_hi:[1,1,0]
	v_pk_fma_f32 v[46:47], v[92:93], v[46:47], v[50:51] op_sel:[0,0,1] op_sel_hi:[1,1,0] neg_lo:[0,0,1] neg_hi:[0,0,1]
	s_nop 0
	v_mov_b32_e32 v47, v53
	v_pk_add_f32 v[46:47], v[46:47], v[210:211]
	s_nop 0
	v_cvt_pk_bf16_f32 v0, v46, v47
	ds_write_b32 v121, v0 offset:26400
	v_pk_mul_f32 v[50:51], v[80:81], v[46:47]
	s_nop 0
	v_pk_fma_f32 v[52:53], v[92:93], v[46:47], v[50:51] op_sel:[0,0,1] op_sel_hi:[1,1,0]
	v_pk_fma_f32 v[46:47], v[92:93], v[46:47], v[50:51] op_sel:[0,0,1] op_sel_hi:[1,1,0] neg_lo:[0,0,1] neg_hi:[0,0,1]
	s_nop 0
	v_mov_b32_e32 v47, v53
	v_pk_add_f32 v[46:47], v[46:47], v[212:213]
	s_nop 0
	v_cvt_pk_bf16_f32 v0, v46, v47
	ds_write_b32 v121, v0 offset:26672
	s_cbranch_vccnz .LBB0_232
	s_load_dwordx2 s[2:3], s[80:81], 0xf0
	v_lshlrev_b32_e32 v0, 2, v54
	s_waitcnt lgkmcnt(0)
	s_add_u32 s2, s2, s0
	s_addc_u32 s3, s3, s1
	s_add_u32 s2, s2, s34
	s_addc_u32 s3, s3, s35
	s_add_u32 s2, s2, s40
	s_addc_u32 s3, s3, s41
	v_lshl_add_u64 v[48:49], s[2:3], 0, v[0:1]
	v_add_co_u32_e32 v50, vcc, 0x4260000, v48
	s_nop 1
	v_addc_co_u32_e32 v51, vcc, 0, v49, vcc
	v_add_co_u32_e32 v48, vcc, 0x4660000, v48
	global_store_dword v[50:51], v46, off
	s_nop 0
	v_addc_co_u32_e32 v49, vcc, 0, v49, vcc
	global_store_dword v[48:49], v47, off
	v_mov_b64_e32 v[46:47], v[72:73]
.LBB0_232:
	v_pk_mul_f32 v[50:51], v[80:81], v[46:47]
	s_and_b64 vcc, exec, s[38:39]
	v_pk_fma_f32 v[52:53], v[92:93], v[46:47], v[50:51] op_sel:[0,0,1] op_sel_hi:[1,1,0] neg_lo:[0,0,1] neg_hi:[0,0,1]
	v_pk_fma_f32 v[46:47], v[92:93], v[46:47], v[50:51] op_sel:[0,0,1] op_sel_hi:[1,1,0]
	s_nop 0
	v_mov_b32_e32 v53, v47
	v_pk_add_f32 v[46:47], v[52:53], v[214:215]
	s_nop 0
	v_cvt_pk_bf16_f32 v0, v46, v47
	ds_write_b32 v121, v0 offset:26944
	v_pk_mul_f32 v[50:51], v[80:81], v[46:47]
	s_nop 0
	v_pk_fma_f32 v[52:53], v[92:93], v[46:47], v[50:51] op_sel:[0,0,1] op_sel_hi:[1,1,0]
	v_pk_fma_f32 v[46:47], v[92:93], v[46:47], v[50:51] op_sel:[0,0,1] op_sel_hi:[1,1,0] neg_lo:[0,0,1] neg_hi:[0,0,1]
	s_nop 0
	v_mov_b32_e32 v47, v53
	v_pk_add_f32 v[46:47], v[46:47], v[216:217]
	s_nop 0
	v_cvt_pk_bf16_f32 v0, v46, v47
	ds_write_b32 v121, v0 offset:27216
	v_pk_mul_f32 v[50:51], v[80:81], v[46:47]
	s_nop 0
	v_pk_fma_f32 v[52:53], v[92:93], v[46:47], v[50:51] op_sel:[0,0,1] op_sel_hi:[1,1,0]
	v_pk_fma_f32 v[46:47], v[92:93], v[46:47], v[50:51] op_sel:[0,0,1] op_sel_hi:[1,1,0] neg_lo:[0,0,1] neg_hi:[0,0,1]
	s_nop 0
	v_mov_b32_e32 v47, v53
	v_pk_add_f32 v[46:47], v[46:47], v[218:219]
	s_nop 0
	v_cvt_pk_bf16_f32 v0, v46, v47
	ds_write_b32 v121, v0 offset:27488
	v_pk_mul_f32 v[50:51], v[80:81], v[46:47]
	s_nop 0
	v_pk_fma_f32 v[52:53], v[92:93], v[46:47], v[50:51] op_sel:[0,0,1] op_sel_hi:[1,1,0]
	v_pk_fma_f32 v[46:47], v[92:93], v[46:47], v[50:51] op_sel:[0,0,1] op_sel_hi:[1,1,0] neg_lo:[0,0,1] neg_hi:[0,0,1]
	s_nop 0
	v_mov_b32_e32 v47, v53
	v_pk_add_f32 v[46:47], v[46:47], v[220:221]
	s_nop 0
	v_cvt_pk_bf16_f32 v0, v46, v47
	ds_write_b32 v121, v0 offset:27760
	s_cbranch_vccnz .LBB0_234
	s_load_dwordx2 s[2:3], s[80:81], 0xf0
	v_lshlrev_b32_e32 v0, 2, v54
	s_waitcnt lgkmcnt(0)
	s_add_u32 s2, s2, s42
	s_addc_u32 s3, s3, s43
	s_add_u32 s2, s2, s34
	s_addc_u32 s3, s3, s35
	s_add_u32 s2, s2, s40
	s_addc_u32 s3, s3, s41
	v_lshl_add_u64 v[48:49], s[2:3], 0, v[0:1]
	v_add_co_u32_e32 v50, vcc, 0x4260000, v48
	s_nop 1
	v_addc_co_u32_e32 v51, vcc, 0, v49, vcc
	v_add_co_u32_e32 v48, vcc, 0x4660000, v48
	global_store_dword v[50:51], v46, off
	s_nop 0
	v_addc_co_u32_e32 v49, vcc, 0, v49, vcc
	global_store_dword v[48:49], v47, off
	v_mov_b64_e32 v[46:47], v[74:75]
.LBB0_234:
	v_pk_mul_f32 v[50:51], v[80:81], v[46:47]
	s_and_b64 vcc, exec, s[38:39]
	v_pk_fma_f32 v[52:53], v[92:93], v[46:47], v[50:51] op_sel:[0,0,1] op_sel_hi:[1,1,0] neg_lo:[0,0,1] neg_hi:[0,0,1]
	v_pk_fma_f32 v[46:47], v[92:93], v[46:47], v[50:51] op_sel:[0,0,1] op_sel_hi:[1,1,0]
	s_nop 0
	v_mov_b32_e32 v53, v47
	s_waitcnt lgkmcnt(8)
	v_pk_add_f32 v[46:47], v[52:53], v[222:223]
	s_nop 0
	v_cvt_pk_bf16_f32 v0, v46, v47
	ds_write_b32 v121, v0 offset:28032
	v_pk_mul_f32 v[50:51], v[80:81], v[46:47]
	s_nop 0
	v_pk_fma_f32 v[52:53], v[92:93], v[46:47], v[50:51] op_sel:[0,0,1] op_sel_hi:[1,1,0]
	v_pk_fma_f32 v[46:47], v[92:93], v[46:47], v[50:51] op_sel:[0,0,1] op_sel_hi:[1,1,0] neg_lo:[0,0,1] neg_hi:[0,0,1]
	s_nop 0
	v_mov_b32_e32 v47, v53
	v_pk_add_f32 v[46:47], v[46:47], v[224:225]
	s_nop 0
	v_cvt_pk_bf16_f32 v0, v46, v47
	ds_write_b32 v121, v0 offset:28304
	v_pk_mul_f32 v[50:51], v[80:81], v[46:47]
	s_nop 0
	v_pk_fma_f32 v[52:53], v[92:93], v[46:47], v[50:51] op_sel:[0,0,1] op_sel_hi:[1,1,0]
	v_pk_fma_f32 v[46:47], v[92:93], v[46:47], v[50:51] op_sel:[0,0,1] op_sel_hi:[1,1,0] neg_lo:[0,0,1] neg_hi:[0,0,1]
	s_nop 0
	v_mov_b32_e32 v47, v53
	v_pk_add_f32 v[46:47], v[46:47], v[226:227]
	s_nop 0
	v_cvt_pk_bf16_f32 v0, v46, v47
	ds_write_b32 v121, v0 offset:28576
	v_pk_mul_f32 v[50:51], v[80:81], v[46:47]
	s_nop 0
	v_pk_fma_f32 v[52:53], v[92:93], v[46:47], v[50:51] op_sel:[0,0,1] op_sel_hi:[1,1,0]
	v_pk_fma_f32 v[46:47], v[92:93], v[46:47], v[50:51] op_sel:[0,0,1] op_sel_hi:[1,1,0] neg_lo:[0,0,1] neg_hi:[0,0,1]
	s_nop 0
	v_mov_b32_e32 v47, v53
	v_pk_add_f32 v[46:47], v[46:47], v[228:229]
	s_nop 0
	v_cvt_pk_bf16_f32 v0, v46, v47
	ds_write_b32 v121, v0 offset:28848
	s_cbranch_vccnz .LBB0_236
	s_load_dwordx2 s[2:3], s[80:81], 0xf0
	v_lshlrev_b32_e32 v0, 2, v54
	s_waitcnt lgkmcnt(0)
	s_add_u32 s2, s2, s44
	s_addc_u32 s3, s3, s45
	s_add_u32 s2, s2, s34
	s_addc_u32 s3, s3, s35
	s_add_u32 s2, s2, s40
	s_addc_u32 s3, s3, s41
	v_lshl_add_u64 v[48:49], s[2:3], 0, v[0:1]
	v_add_co_u32_e32 v50, vcc, 0x4260000, v48
	s_nop 1
	v_addc_co_u32_e32 v51, vcc, 0, v49, vcc
	v_add_co_u32_e32 v48, vcc, 0x4660000, v48
	global_store_dword v[50:51], v46, off
	s_nop 0
	v_addc_co_u32_e32 v49, vcc, 0, v49, vcc
	global_store_dword v[48:49], v47, off
	v_mov_b64_e32 v[46:47], v[76:77]
.LBB0_236:
	v_pk_mul_f32 v[50:51], v[78:79], v[46:47]
	v_mul_f32_e32 v0, v96, v46
	v_sub_f32_e32 v46, v50, v51
	v_fmac_f32_e32 v0, v78, v47
	v_add_f32_e32 v48, v46, v230
	v_add_f32_e32 v0, v0, v231
	v_cvt_pk_bf16_f32 v46, v48, v0
	ds_write_b32 v121, v46 offset:29120
	v_mul_f32_e32 v49, v78, v48
	v_mul_f32_e32 v50, v78, v0
	v_fma_f32 v0, -v96, v0, v49
	v_fmac_f32_e32 v50, v96, v48
	v_add_f32_e32 v0, v0, v232
	v_add_f32_e32 v48, v50, v233
	v_cvt_pk_bf16_f32 v46, v0, v48
	ds_write_b32 v121, v46 offset:29392
	v_mul_f32_e32 v49, v78, v0
	v_fma_f32 v49, -v96, v48, v49
	s_and_b64 vcc, exec, s[38:39]
	v_add_f32_e32 v49, v49, v234
	v_mul_f32_e32 v46, v78, v48
	v_fmac_f32_e32 v46, v96, v0
	v_add_f32_e32 v0, v46, v235
	v_cvt_pk_bf16_f32 v46, v49, v0
	ds_write_b32 v121, v46 offset:29664
	v_mul_f32_e32 v48, v78, v49
	v_fma_f32 v48, -v96, v0, v48
	v_mul_f32_e32 v0, v78, v0
	v_fmac_f32_e32 v0, v96, v49
	v_add_f32_e32 v97, v48, v236
	v_add_f32_e32 v124, v0, v237
	v_cvt_pk_bf16_f32 v0, v97, v124
	ds_write_b32 v121, v0 offset:29936
	s_cbranch_vccnz .LBB0_238
	s_load_dwordx2 s[2:3], s[80:81], 0xf0
	v_lshlrev_b32_e32 v0, 2, v54
	s_waitcnt lgkmcnt(0)
	s_add_u32 s2, s2, s46
	s_addc_u32 s3, s3, s47
	s_add_u32 s2, s2, s34
	s_addc_u32 s3, s3, s35
	s_add_u32 s2, s2, s40
	s_addc_u32 s3, s3, s41
	v_lshl_add_u64 v[46:47], s[2:3], 0, v[0:1]
	v_add_co_u32_e32 v48, vcc, 0x4260000, v46
	s_nop 1
	v_addc_co_u32_e32 v49, vcc, 0, v47, vcc
	v_add_co_u32_e32 v46, vcc, 0x4660000, v46
	global_store_dword v[48:49], v97, off
	s_nop 0
	v_addc_co_u32_e32 v47, vcc, 0, v47, vcc
	global_store_dword v[46:47], v124, off
